# stack on the m2a version: chunk-boundary decay load issued before the state MFMAs (retention + SSD units) and SSD tile staging loads issued ahead of the tile loop
# baseline (speedup 1.0000x reference)
; template <int DQK, int DV, int MODE, int VR> ...
;     ...
;     AT_STORE(jfirst & 1);
;     __syncthreads();
;     for (int j = jfirst; j < ntiles; ++j) {
;         if (j + 1 < ntiles) AT_LOAD(j + 1);
.LBB0_661:
	s_or_b64 exec, exec, s[2:3]
	v_lshlrev_b32_e32 v101, 4, v179
	s_and_saveexec_b64 s[2:3], s[6:7]
	v_add_u32_e32 v0, 16, v101
	ds_write_b128 v0, v[94:97] offset:26624
	s_or_b64 exec, exec, s[2:3]
	s_lshl_b32 s14, s12, 2
	s_lshl_b32 s19, s13, 12
	s_add_i32 s21, s14, 4
	s_or_b32 s20, s16, 31
	s_lshl_b64 s[2:3], s[86:87], 7
	s_add_u32 s2, s11, s2
	s_addc_u32 s3, 0, s3
	v_readlane_b32 s4, v255, 47
	s_add_u32 s2, s4, s2
	v_readlane_b32 s4, v255, 48
	s_addc_u32 s3, s4, s3
	s_lshl_b64 s[8:9], s[86:87], 2
	v_readlane_b32 s4, v255, 49
	s_add_u32 s4, s4, s8
	v_readlane_b32 s5, v255, 50
	v_lshlrev_b32_e32 v107, 3, v35
	v_lshlrev_b32_e32 v0, 1, v179
	v_lshrrev_b32_e32 v35, 1, v179
	s_addc_u32 s5, s5, s9
	v_and_b32_e32 v0, 8, v0
	v_and_b32_e32 v35, 4, v35
	v_and_b32_e32 v36, 19, v179
	s_add_u32 s8, s4, s10
	v_or3_b32 v0, v0, v36, v35
	v_lshlrev_b32_e32 v36, 2, v179
	s_addc_u32 s9, s5, 0
	v_ashrrev_i32_e32 v37, 31, v36
	s_add_u32 s22, s86, 64
	v_and_b32_e32 v106, 63, v179
	v_mul_u32_u24_e32 v109, 0x110, v0
	v_mul_u32_u24_e32 v108, 0x90, v34
	v_add_u32_e32 v0, s86, v107
	v_lshl_add_u64 v[102:103], v[36:37], 2, s[8:9]
	s_addc_u32 s23, 0, 0
	s_mov_b64 s[8:9], 0
	s_add_u32 s98, s2, 0x0
	s_addc_u32 s99, s3, 0
	v_mov_b32_e32 v204, v179
	s_add_u32 s12, s22, 0
	v_ashrrev_i32_e32 v205, 31, v204
	v_lshrrev_b32_e32 v206, 28, v205
	v_add_u32_e32 v208, v204, v206
	v_ashrrev_i32_e32 v206, 4, v208
	v_ashrrev_i32_e32 v207, 31, v206
	s_addc_u32 s13, s23, 0
	v_and_b32_e32 v208, 0x1ffffff0, v208
	v_lshl_add_u64 v[206:207], s[12:13], 0, v[206:207]
	v_sub_u32_e32 v208, v204, v208
	v_lshlrev_b64 v[206:207], 10, v[206:207]
	v_lshlrev_b32_e32 v208, 3, v208
	v_lshl_add_u64 v[206:207], s[0:1], 0, v[206:207]
	v_ashrrev_i32_e32 v209, 31, v208
	v_add_u32_e32 v210, 0x200, v204
	v_lshl_add_u64 v[206:207], v[208:209], 1, v[206:207]
	v_ashrrev_i32_e32 v208, 31, v210
	v_lshrrev_b32_e32 v208, 28, v208
	v_add_u32_e32 v211, v210, v208
	v_ashrrev_i32_e32 v208, 4, v211
	v_ashrrev_i32_e32 v209, 31, v208
	v_and_b32_e32 v211, 0x1ffffff0, v211
	v_lshl_add_u64 v[208:209], s[12:13], 0, v[208:209]
	v_sub_u32_e32 v210, v210, v211
	v_lshlrev_b64 v[208:209], 10, v[208:209]
	v_lshlrev_b32_e32 v210, 3, v210
	v_lshl_add_u64 v[208:209], s[0:1], 0, v[208:209]
	v_ashrrev_i32_e32 v211, 31, v210
	v_lshl_add_u64 v[208:209], v[210:211], 1, v[208:209]
	global_load_dwordx4 v[140:143], v[206:207], off
	global_load_dwordx4 v[144:147], v[208:209], off
	v_cmp_gt_i32_e32 vcc, s41, v204
	s_and_saveexec_b64 s[12:13], vcc
	s_cbranch_execz .Lssdpf0_a
	v_lshrrev_b32_e32 v205, 26, v205
	v_add_u32_e32 v205, v204, v205
	v_and_b32_e32 v205, 0xffffffc0, v205
	v_sub_u32_e32 v204, v204, v205
	v_lshrrev_b16_sdwa v206, v230, sext(v204) dst_sel:DWORD dst_unused:UNUSED_PAD src0_sel:DWORD src1_sel:BYTE_0
	v_and_b32_e32 v206, 31, v206
	v_add_u16_e32 v206, v204, v206
	v_ashrrev_i16_sdwa v207, v231, sext(v206) dst_sel:DWORD dst_unused:UNUSED_PAD src0_sel:DWORD src1_sel:BYTE_0
	v_and_b32_e32 v206, 0xe0, v206
	v_sub_u16_e32 v204, v204, v206
	v_lshlrev_b32_sdwa v204, v197, sext(v204) dst_sel:DWORD dst_unused:UNUSED_PAD src0_sel:DWORD src1_sel:BYTE_0
	v_add_u16_e32 v204, v204, v207
	v_lshlrev_b32_e32 v208, 5, v207
	v_ashrrev_i16_e32 v204, 1, v204
	v_and_or_b32 v205, v208, 32, v205
	v_bfe_i32 v204, v204, 0, 16
	v_add_lshl_u32 v204, v205, v204, 3
	v_ashrrev_i32_e32 v205, 31, v204
	v_lshl_add_u64 v[204:205], v[204:205], 1, s[98:99]
	global_load_dwordx4 v[148:151], v[204:205], off
.Lssdpf0_a:
	s_or_b64 exec, exec, s[12:13]
	s_and_saveexec_b64 s[12:13], s[6:7]
	s_cbranch_execz .Lssdpf0_b
	global_load_dwordx4 v[152:155], v[102:103], off
.Lssdpf0_b:
	s_or_b64 exec, exec, s[12:13]
	s_add_u32 s98, s2, 0x2000
	s_addc_u32 s99, s3, 0
	v_mov_b32_e32 v204, v179
	s_add_u32 s12, s22, 64
	v_ashrrev_i32_e32 v205, 31, v204
	v_lshrrev_b32_e32 v206, 28, v205
	v_add_u32_e32 v208, v204, v206
	v_ashrrev_i32_e32 v206, 4, v208
	v_ashrrev_i32_e32 v207, 31, v206
	s_addc_u32 s13, s23, 0
	v_and_b32_e32 v208, 0x1ffffff0, v208
	v_lshl_add_u64 v[206:207], s[12:13], 0, v[206:207]
	v_sub_u32_e32 v208, v204, v208
	v_lshlrev_b64 v[206:207], 10, v[206:207]
	v_lshlrev_b32_e32 v208, 3, v208
	v_lshl_add_u64 v[206:207], s[0:1], 0, v[206:207]
	v_ashrrev_i32_e32 v209, 31, v208
	v_add_u32_e32 v210, 0x200, v204
	v_lshl_add_u64 v[206:207], v[208:209], 1, v[206:207]
	v_ashrrev_i32_e32 v208, 31, v210
	v_lshrrev_b32_e32 v208, 28, v208
	v_add_u32_e32 v211, v210, v208
	v_ashrrev_i32_e32 v208, 4, v211
	v_ashrrev_i32_e32 v209, 31, v208
	v_and_b32_e32 v211, 0x1ffffff0, v211
	v_lshl_add_u64 v[208:209], s[12:13], 0, v[208:209]
	v_sub_u32_e32 v210, v210, v211
	v_lshlrev_b64 v[208:209], 10, v[208:209]
	v_lshlrev_b32_e32 v210, 3, v210
	v_lshl_add_u64 v[208:209], s[0:1], 0, v[208:209]
	v_ashrrev_i32_e32 v211, 31, v210
	v_lshl_add_u64 v[208:209], v[210:211], 1, v[208:209]
	global_load_dwordx4 v[156:159], v[206:207], off
	global_load_dwordx4 v[160:163], v[208:209], off
	v_cmp_gt_i32_e32 vcc, s41, v204
	s_and_saveexec_b64 s[12:13], vcc
	s_cbranch_execz .Lssdpf1_a
	v_lshrrev_b32_e32 v205, 26, v205
	v_add_u32_e32 v205, v204, v205
	v_and_b32_e32 v205, 0xffffffc0, v205
	v_sub_u32_e32 v204, v204, v205
	v_lshrrev_b16_sdwa v206, v230, sext(v204) dst_sel:DWORD dst_unused:UNUSED_PAD src0_sel:DWORD src1_sel:BYTE_0
	v_and_b32_e32 v206, 31, v206
	v_add_u16_e32 v206, v204, v206
	v_ashrrev_i16_sdwa v207, v231, sext(v206) dst_sel:DWORD dst_unused:UNUSED_PAD src0_sel:DWORD src1_sel:BYTE_0
	v_and_b32_e32 v206, 0xe0, v206
	v_sub_u16_e32 v204, v204, v206
	v_lshlrev_b32_sdwa v204, v197, sext(v204) dst_sel:DWORD dst_unused:UNUSED_PAD src0_sel:DWORD src1_sel:BYTE_0
	v_add_u16_e32 v204, v204, v207
	v_lshlrev_b32_e32 v208, 5, v207
	v_ashrrev_i16_e32 v204, 1, v204
	v_and_or_b32 v205, v208, 32, v205
	v_bfe_i32 v204, v204, 0, 16
	v_add_lshl_u32 v204, v205, v204, 3
	v_ashrrev_i32_e32 v205, 31, v204
	v_lshl_add_u64 v[204:205], v[204:205], 1, s[98:99]
	global_load_dwordx4 v[164:167], v[204:205], off
; __device__ __forceinline__ float ex2(float x) { return __builtin_amdgcn_exp2f(x); }
; #define MFMA32(a, b, c) __builtin_amdgcn_mfma_f32_32x32x16_bf16((a), (b), (c), 0, 0, 0)
; template <int DQK, int DV, int MODE, int VR> ...
;     ...
;     for (int j = jfirst; j < ntiles; ++j) {
;         if (j + 1 < ntiles) AT_LOAD(j + 1);
;         const int kv0 = 64 * j;
;         if (kv0 <= t0 + 31) {
;             const unsigned char* Kl = lds + (j & 1) * STG; const unsigned char* Vl = Kl + KBYTES; const float* Al = (const float*)(Vl + VBYTES);
;     ...
; #pragma unroll
;                 for (int kb = 0; kb < 2; ++kb) {
;                     if (kv0 + 32 * kb > t0 + 31) continue;
;                     f32x16 p;
; #pragma unroll
;                     for (int r = 0; r < 16; ++r) p[r] = 0.f;
; #pragma unroll
;                     for (int ks = 0; ks < NKS; ++ks) { const bf16x8 a = *(const bf16x8*)(Kl + (32 * kb + pirow) * KSTR + (16 * ks + 8 * hi) * 2); p = MFMA32(a, qf[ks], p); }
;                     bf16x8 pb[2];
; #pragma unroll
;                     for (int sl = 0; sl < 2; ++sl) {
;                         const f32x4 s0 = *(const f32x4*)(Al + 32 * kb + 16 * sl + 8 * hi), s1 = *(const f32x4*)(Al + 32 * kb + 16 * sl + 8 * hi + 4);
;                         float e[8];
; #pragma unroll
;                         for (int jj = 0; jj < 8; ++jj) { const float as = jj < 4 ? s0[jj] : s1[jj - 4]; const int kv = kv0 + 32 * kb + 16 * sl + 8 * hi + jj;
;                             const float w = ex2(a2t - as); e[jj] = (diag && kv > t) ? 0.f : p[8 * sl + jj] * w; }
.Lssdpf1_a:
	s_or_b64 exec, exec, s[12:13]
	s_and_saveexec_b64 s[12:13], s[6:7]
	s_cbranch_execz .Lssdpf1_b
	global_load_dwordx4 v[168:171], v[102:103], off offset:256
.Lssdpf1_b:
	s_or_b64 exec, exec, s[12:13]
	s_add_u32 s98, s2, 0x4000
	s_addc_u32 s99, s3, 0
	v_mov_b32_e32 v204, v179
	s_add_u32 s12, s22, 128
	v_ashrrev_i32_e32 v205, 31, v204
	v_lshrrev_b32_e32 v206, 28, v205
	v_add_u32_e32 v208, v204, v206
	v_ashrrev_i32_e32 v206, 4, v208
	v_ashrrev_i32_e32 v207, 31, v206
	s_addc_u32 s13, s23, 0
	v_and_b32_e32 v208, 0x1ffffff0, v208
	v_lshl_add_u64 v[206:207], s[12:13], 0, v[206:207]
	v_sub_u32_e32 v208, v204, v208
	v_lshlrev_b64 v[206:207], 10, v[206:207]
	v_lshlrev_b32_e32 v208, 3, v208
	v_lshl_add_u64 v[206:207], s[0:1], 0, v[206:207]
	v_ashrrev_i32_e32 v209, 31, v208
	v_add_u32_e32 v210, 0x200, v204
	v_lshl_add_u64 v[206:207], v[208:209], 1, v[206:207]
	v_ashrrev_i32_e32 v208, 31, v210
	v_lshrrev_b32_e32 v208, 28, v208
	v_add_u32_e32 v211, v210, v208
	v_ashrrev_i32_e32 v208, 4, v211
	v_ashrrev_i32_e32 v209, 31, v208
	v_and_b32_e32 v211, 0x1ffffff0, v211
	v_lshl_add_u64 v[208:209], s[12:13], 0, v[208:209]
	v_sub_u32_e32 v210, v210, v211
	v_lshlrev_b64 v[208:209], 10, v[208:209]
	v_lshlrev_b32_e32 v210, 3, v210
	v_lshl_add_u64 v[208:209], s[0:1], 0, v[208:209]
	v_ashrrev_i32_e32 v211, 31, v210
	v_lshl_add_u64 v[208:209], v[210:211], 1, v[208:209]
	global_load_dwordx4 v[182:185], v[206:207], off
	global_load_dwordx4 v[186:189], v[208:209], off
	v_cmp_gt_i32_e32 vcc, s41, v204
	s_and_saveexec_b64 s[12:13], vcc
	s_cbranch_execz .Lssdpf2_a
	v_lshrrev_b32_e32 v205, 26, v205
	v_add_u32_e32 v205, v204, v205
	v_and_b32_e32 v205, 0xffffffc0, v205
	v_sub_u32_e32 v204, v204, v205
	v_lshrrev_b16_sdwa v206, v230, sext(v204) dst_sel:DWORD dst_unused:UNUSED_PAD src0_sel:DWORD src1_sel:BYTE_0
	v_and_b32_e32 v206, 31, v206
	v_add_u16_e32 v206, v204, v206
	v_ashrrev_i16_sdwa v207, v231, sext(v206) dst_sel:DWORD dst_unused:UNUSED_PAD src0_sel:DWORD src1_sel:BYTE_0
	v_and_b32_e32 v206, 0xe0, v206
	v_sub_u16_e32 v204, v204, v206
	v_lshlrev_b32_sdwa v204, v197, sext(v204) dst_sel:DWORD dst_unused:UNUSED_PAD src0_sel:DWORD src1_sel:BYTE_0
	v_add_u16_e32 v204, v204, v207
	v_lshlrev_b32_e32 v208, 5, v207
	v_ashrrev_i16_e32 v204, 1, v204
	v_and_or_b32 v205, v208, 32, v205
	v_bfe_i32 v204, v204, 0, 16
	v_add_lshl_u32 v204, v205, v204, 3
	v_ashrrev_i32_e32 v205, 31, v204
	v_lshl_add_u64 v[204:205], v[204:205], 1, s[98:99]
	global_load_dwordx4 v[190:193], v[204:205], off
.Lssdpf2_a:
	s_or_b64 exec, exec, s[12:13]
	s_and_saveexec_b64 s[12:13], s[6:7]
	s_cbranch_execz .Lssdpf2_b
	global_load_dwordx4 v[244:247], v[102:103], off offset:512
.Lssdpf2_b:
	s_or_b64 exec, exec, s[12:13]
	s_waitcnt lgkmcnt(0)
	s_barrier
.LBB0_664:
	s_add_i32 s24, s14, 1
	s_cmp_lt_u32 s24, s21
	s_cselect_b64 s[10:11], -1, 0
.LBB0_670:
	s_add_u32 s25, s86, s8
	s_cmp_gt_i32 s25, s20
	s_cbranch_scc1 .LBB0_673
	s_bitcmp1_b32 s14, 0
	s_cselect_b32 s4, 0x6900, 0
	s_add_i32 s26, s4, 16
	v_add_u32_e32 v34, s26, v100
	v_add_u32_e32 v111, v34, v109
	v_add_u32_e32 v110, v34, v100
	ds_read_b128 v[34:37], v111
	ds_read_b128 v[112:115], v111 offset:32
	v_lshl_add_u64 v[104:105], v[0:1], 0, s[8:9]
	s_add_i32 s4, s25, 63
	s_waitcnt lgkmcnt(1)
	v_mfma_f32_32x32x16_bf16 v[34:49], v[34:37], v[74:77], 0
	s_cmp_gt_i32 s4, s16
	s_cselect_b64 s[12:13], -1, 0
	v_cmp_gt_i32_e32 vcc, v104, v98
	s_and_b64 s[14:15], s[12:13], vcc
	v_cmp_ge_i32_e32 vcc, v104, v98
	s_add_i32 s25, s25, 32
	s_waitcnt lgkmcnt(0)
	v_mfma_f32_32x32x16_bf16 v[34:49], v[112:115], v[78:81], v[34:49]
	ds_read_b128 v[212:215], v111 offset:64
	ds_read_b128 v[216:219], v111 offset:96
	ds_read_b128 v[220:223], v111 offset:128
	s_waitcnt lgkmcnt(2)
	v_mfma_f32_32x32x16_bf16 v[34:49], v[212:215], v[70:73], v[34:49]
	ds_read_b128 v[212:215], v111 offset:160
	s_waitcnt lgkmcnt(2)
	v_mfma_f32_32x32x16_bf16 v[34:49], v[216:219], v[66:69], v[34:49]
	ds_read_b128 v[216:219], v111 offset:192
	s_waitcnt lgkmcnt(2)
	v_mfma_f32_32x32x16_bf16 v[34:49], v[220:223], v[62:65], v[34:49]
	ds_read_b128 v[220:223], v111 offset:224
	s_waitcnt lgkmcnt(2)
	v_mfma_f32_32x32x16_bf16 v[34:49], v[212:215], v[58:61], v[34:49]
	s_waitcnt lgkmcnt(1)
	v_mfma_f32_32x32x16_bf16 v[34:49], v[216:219], v[54:57], v[34:49]
	s_waitcnt lgkmcnt(0)
	v_mfma_f32_32x32x16_bf16 v[34:49], v[220:223], v[50:53], v[34:49]
	ds_read_b128 v[112:115], v110 offset:26624
	ds_read_b128 v[116:119], v110 offset:26640
	s_waitcnt lgkmcnt(1)
	v_sub_f32_e32 v105, v99, v112
	v_exp_f32_e32 v105, v105
	v_add_u32_e32 v112, 2, v104
	s_nop 5
	v_mul_f32_e32 v34, v34, v105
	v_sub_f32_e32 v105, v99, v113
	v_exp_f32_e32 v105, v105
	v_cndmask_b32_e64 v34, v34, 0, s[14:15]
	s_and_b64 s[14:15], s[12:13], vcc
	v_cmp_gt_i32_e32 vcc, v112, v98
	v_mul_f32_e32 v35, v35, v105
	v_sub_f32_e32 v105, v99, v114
	v_exp_f32_e32 v105, v105
	v_add_u32_e32 v112, 3, v104
	v_cndmask_b32_e64 v35, v35, 0, s[14:15]
	s_and_b64 s[14:15], s[12:13], vcc
	v_mul_f32_e32 v36, v36, v105
	v_sub_f32_e32 v105, v99, v115
	v_exp_f32_e32 v105, v105
	v_cmp_gt_i32_e32 vcc, v112, v98
	v_add_u32_e32 v112, 4, v104
	v_cndmask_b32_e64 v36, v36, 0, s[14:15]
	v_mul_f32_e32 v37, v37, v105
	s_waitcnt lgkmcnt(0)
; __device__ __forceinline__ unsigned pk2(float lo, float hi) { f32x2 v = {lo, hi}; bf16x2_t b = __builtin_convertvector(v, bf16x2_t); return __builtin_bit_cast(unsigned, b); }
; __device__ __forceinline__ float ex2(float x) { return __builtin_amdgcn_exp2f(x); }
; #define MFMA32(a, b, c) __builtin_amdgcn_mfma_f32_32x32x16_bf16((a), (b), (c), 0, 0, 0)
; template <int DQK, int DV, int MODE, int VR> ...
;     ...
; #pragma unroll
;                 for (int kb = 0; kb < 2; ++kb) {
;                     if (kv0 + 32 * kb > t0 + 31) continue;
;                     f32x16 p;
; #pragma unroll
;                     for (int r = 0; r < 16; ++r) p[r] = 0.f;
; #pragma unroll
;                     for (int ks = 0; ks < NKS; ++ks) { const bf16x8 a = *(const bf16x8*)(Kl + (32 * kb + pirow) * KSTR + (16 * ks + 8 * hi) * 2); p = MFMA32(a, qf[ks], p); }
;                     bf16x8 pb[2];
; #pragma unroll
;                     for (int sl = 0; sl < 2; ++sl) {
;                         const f32x4 s0 = *(const f32x4*)(Al + 32 * kb + 16 * sl + 8 * hi), s1 = *(const f32x4*)(Al + 32 * kb + 16 * sl + 8 * hi + 4);
;                         float e[8];
; #pragma unroll
;                         for (int jj = 0; jj < 8; ++jj) { const float as = jj < 4 ? s0[jj] : s1[jj - 4]; const int kv = kv0 + 32 * kb + 16 * sl + 8 * hi + jj;
;                             const float w = ex2(a2t - as); e[jj] = (diag && kv > t) ? 0.f : p[8 * sl + jj] * w; }
;                         u32x4 w; w.x = pk2(e[0], e[1]); w.y = pk2(e[2], e[3]); w.z = pk2(e[4], e[5]); w.w = pk2(e[6], e[7]);
;                         pb[sl] = __builtin_bit_cast(bf16x8, w);
;                     }
; #pragma unroll
;                     for (int b = 0; b < NBLK; ++b)
; #pragma unroll
;                         for (int sl = 0; sl < 2; ++sl) { const bf16x8 a = *(const bf16x8*)(Vl + (32 * b + r32) * VSTR + (32 * kb + 16 * sl + 8 * hi) * 2); o[b] = MFMA32(a, pb[sl], o[b]); }
	v_sub_f32_e32 v105, v99, v116
	v_exp_f32_e32 v105, v105
	s_and_b64 s[14:15], s[12:13], vcc
	v_cmp_gt_i32_e32 vcc, v112, v98
	v_add_u32_e32 v112, 5, v104
	v_mul_f32_e32 v38, v38, v105
	v_sub_f32_e32 v105, v99, v117
	v_exp_f32_e32 v105, v105
	v_cndmask_b32_e64 v37, v37, 0, s[14:15]
	s_and_b64 s[14:15], s[12:13], vcc
	v_cmp_gt_i32_e32 vcc, v112, v98
	v_mul_f32_e32 v39, v39, v105
	v_sub_f32_e32 v105, v99, v118
	v_exp_f32_e32 v105, v105
	v_add_u32_e32 v112, 6, v104
	v_cndmask_b32_e64 v38, v38, 0, s[14:15]
	s_and_b64 s[14:15], s[12:13], vcc
	v_mul_f32_e32 v40, v40, v105
	v_sub_f32_e32 v105, v99, v119
	v_exp_f32_e32 v105, v105
	v_cmp_gt_i32_e32 vcc, v112, v98
	v_add_u32_e32 v112, 7, v104
	v_cndmask_b32_e64 v39, v39, 0, s[14:15]
	s_and_b64 s[14:15], s[12:13], vcc
	v_cmp_gt_i32_e32 vcc, v112, v98
	v_cndmask_b32_e64 v40, v40, 0, s[14:15]
	s_and_b64 s[14:15], s[12:13], vcc
	v_mul_f32_e32 v41, v41, v105
	v_cndmask_b32_e64 v41, v41, 0, s[14:15]
	v_cvt_pk_bf16_f32 v34, v34, v35
	v_cvt_pk_bf16_f32 v35, v36, v37
	v_cvt_pk_bf16_f32 v36, v38, v39
	v_cvt_pk_bf16_f32 v37, v40, v41
	ds_read_b128 v[38:41], v110 offset:26688
	ds_read_b128 v[112:115], v110 offset:26704
	v_add_u32_e32 v105, 16, v104
	v_cmp_gt_i32_e32 vcc, v105, v98
	s_and_b64 s[14:15], s[12:13], vcc
	s_waitcnt lgkmcnt(1)
	v_sub_f32_e32 v38, v99, v38
	v_exp_f32_e32 v38, v38
	v_sub_f32_e32 v39, v99, v39
	v_exp_f32_e32 v39, v39
	v_sub_f32_e32 v40, v99, v40
	v_mul_f32_e32 v38, v42, v38
	v_add_u32_e32 v42, 17, v104
	v_cmp_gt_i32_e32 vcc, v42, v98
	v_add_u32_e32 v42, 18, v104
	v_cndmask_b32_e64 v38, v38, 0, s[14:15]
	s_and_b64 s[14:15], s[12:13], vcc
	v_mul_f32_e32 v39, v43, v39
	v_exp_f32_e32 v40, v40
	v_cmp_gt_i32_e32 vcc, v42, v98
	v_sub_f32_e32 v41, v99, v41
	v_add_u32_e32 v42, 19, v104
	v_cndmask_b32_e64 v39, v39, 0, s[14:15]
	s_and_b64 s[14:15], s[12:13], vcc
	v_exp_f32_e32 v41, v41
	v_cmp_gt_i32_e32 vcc, v42, v98
	s_waitcnt lgkmcnt(0)
	v_sub_f32_e32 v42, v99, v112
	v_exp_f32_e32 v42, v42
	v_mul_f32_e32 v40, v44, v40
	v_add_u32_e32 v43, 20, v104
	v_cndmask_b32_e64 v40, v40, 0, s[14:15]
	s_and_b64 s[14:15], s[12:13], vcc
	v_mul_f32_e32 v41, v45, v41
	v_cmp_gt_i32_e32 vcc, v43, v98
	v_sub_f32_e32 v43, v99, v113
	v_add_u32_e32 v44, 21, v104
	v_cndmask_b32_e64 v41, v41, 0, s[14:15]
	s_and_b64 s[14:15], s[12:13], vcc
	v_mul_f32_e32 v42, v46, v42
	v_exp_f32_e32 v43, v43
	v_cmp_gt_i32_e32 vcc, v44, v98
	v_sub_f32_e32 v44, v99, v114
	v_add_u32_e32 v45, 22, v104
	v_cndmask_b32_e64 v42, v42, 0, s[14:15]
	s_and_b64 s[14:15], s[12:13], vcc
	v_exp_f32_e32 v44, v44
	v_cmp_gt_i32_e32 vcc, v45, v98
	v_sub_f32_e32 v45, v99, v115
	v_exp_f32_e32 v45, v45
	v_mul_f32_e32 v43, v47, v43
	v_add_u32_e32 v46, 23, v104
	v_cndmask_b32_e64 v43, v43, 0, s[14:15]
	s_and_b64 s[14:15], s[12:13], vcc
	v_mul_f32_e32 v44, v48, v44
	v_cmp_gt_i32_e32 vcc, v46, v98
	v_cndmask_b32_e64 v44, v44, 0, s[14:15]
	s_and_b64 s[14:15], s[12:13], vcc
	v_mul_f32_e32 v45, v49, v45
	v_cvt_pk_bf16_f32 v38, v38, v39
	v_cvt_pk_bf16_f32 v39, v40, v41
	v_cvt_pk_bf16_f32 v40, v42, v43
	v_add_u32_e32 v42, s26, v108
	v_cndmask_b32_e64 v45, v45, 0, s[14:15]
	v_add_u32_e32 v105, v42, v100
	v_cvt_pk_bf16_f32 v41, v44, v45
	ds_read_b128 v[42:45], v105 offset:17408
	ds_read_b128 v[46:49], v105 offset:17440
	s_waitcnt lgkmcnt(1)
	v_mfma_f32_32x32x16_bf16 v[2:17], v[42:45], v[34:37], v[2:17]
	ds_read_b128 v[42:45], v105 offset:22016
	s_cmp_gt_i32 s25, s20
	s_waitcnt lgkmcnt(0)
	v_mfma_f32_32x32x16_bf16 v[18:33], v[42:45], v[34:37], v[18:33]
	ds_read_b128 v[34:37], v105 offset:22048
	v_mfma_f32_32x32x16_bf16 v[2:17], v[46:49], v[38:41], v[2:17]
	s_waitcnt lgkmcnt(0)
	v_mfma_f32_32x32x16_bf16 v[18:33], v[34:37], v[38:41], v[18:33]
	s_cbranch_scc1 .LBB0_673
	ds_read_b128 v[34:37], v111 offset:8704
	ds_read_b128 v[112:115], v111 offset:8736
	s_waitcnt lgkmcnt(1)
	v_mfma_f32_32x32x16_bf16 v[34:49], v[34:37], v[74:77], 0
	s_waitcnt lgkmcnt(0)
	v_mfma_f32_32x32x16_bf16 v[34:49], v[112:115], v[78:81], v[34:49]
	ds_read_b128 v[212:215], v111 offset:8768
	ds_read_b128 v[216:219], v111 offset:8800
	ds_read_b128 v[220:223], v111 offset:8832
	s_waitcnt lgkmcnt(2)
	v_mfma_f32_32x32x16_bf16 v[34:49], v[212:215], v[70:73], v[34:49]
	ds_read_b128 v[212:215], v111 offset:8864
	s_waitcnt lgkmcnt(2)
	v_mfma_f32_32x32x16_bf16 v[34:49], v[216:219], v[66:69], v[34:49]
	ds_read_b128 v[216:219], v111 offset:8896
	s_waitcnt lgkmcnt(2)
	v_mfma_f32_32x32x16_bf16 v[34:49], v[220:223], v[62:65], v[34:49]
	ds_read_b128 v[220:223], v111 offset:8928
	s_waitcnt lgkmcnt(2)
	v_mfma_f32_32x32x16_bf16 v[34:49], v[212:215], v[58:61], v[34:49]
	s_waitcnt lgkmcnt(1)
	v_mfma_f32_32x32x16_bf16 v[34:49], v[216:219], v[54:57], v[34:49]
	v_add_u32_e32 v111, 32, v104
	v_cmp_gt_i32_e32 vcc, v111, v98
	s_and_b64 s[14:15], s[12:13], vcc
	v_cmp_ge_i32_e32 vcc, v111, v98
	s_waitcnt lgkmcnt(0)
	v_mfma_f32_32x32x16_bf16 v[34:49], v[220:223], v[50:53], v[34:49]
	ds_read_b128 v[112:115], v110 offset:26752
	ds_read_b128 v[116:119], v110 offset:26768
	s_waitcnt lgkmcnt(1)
	v_sub_f32_e32 v111, v99, v114
	v_exp_f32_e32 v111, v111
	v_sub_f32_e32 v112, v99, v112
	v_exp_f32_e32 v112, v112
	v_add_u32_e32 v114, 48, v104
	s_nop 3
	v_mul_f32_e32 v36, v36, v111
	v_sub_f32_e32 v111, v99, v115
	v_exp_f32_e32 v111, v111
	v_mul_f32_e32 v34, v34, v112
	v_sub_f32_e32 v112, v99, v113
	v_exp_f32_e32 v112, v112
	v_mul_f32_e32 v37, v37, v111
	s_waitcnt lgkmcnt(0)
; __device__ __forceinline__ unsigned pk2(float lo, float hi) { f32x2 v = {lo, hi}; bf16x2_t b = __builtin_convertvector(v, bf16x2_t); return __builtin_bit_cast(unsigned, b); }
; __device__ __forceinline__ float ex2(float x) { return __builtin_amdgcn_exp2f(x); }
; #define MFMA32(a, b, c) __builtin_amdgcn_mfma_f32_32x32x16_bf16((a), (b), (c), 0, 0, 0)
; template <int DQK, int DV, int MODE, int VR> ...
;     ...
; #pragma unroll
;                 for (int kb = 0; kb < 2; ++kb) {
;                     if (kv0 + 32 * kb > t0 + 31) continue;
;                     f32x16 p;
; #pragma unroll
;                     for (int r = 0; r < 16; ++r) p[r] = 0.f;
; #pragma unroll
;                     for (int ks = 0; ks < NKS; ++ks) { const bf16x8 a = *(const bf16x8*)(Kl + (32 * kb + pirow) * KSTR + (16 * ks + 8 * hi) * 2); p = MFMA32(a, qf[ks], p); }
;                     bf16x8 pb[2];
; #pragma unroll
;                     for (int sl = 0; sl < 2; ++sl) {
;                         const f32x4 s0 = *(const f32x4*)(Al + 32 * kb + 16 * sl + 8 * hi), s1 = *(const f32x4*)(Al + 32 * kb + 16 * sl + 8 * hi + 4);
;                         float e[8];
; #pragma unroll
;                         for (int jj = 0; jj < 8; ++jj) { const float as = jj < 4 ? s0[jj] : s1[jj - 4]; const int kv = kv0 + 32 * kb + 16 * sl + 8 * hi + jj;
;                             const float w = ex2(a2t - as); e[jj] = (diag && kv > t) ? 0.f : p[8 * sl + jj] * w; }
;                         u32x4 w; w.x = pk2(e[0], e[1]); w.y = pk2(e[2], e[3]); w.z = pk2(e[4], e[5]); w.w = pk2(e[6], e[7]);
;                         pb[sl] = __builtin_bit_cast(bf16x8, w);
;                     }
; #pragma unroll
;                     for (int b = 0; b < NBLK; ++b)
; #pragma unroll
;                         for (int sl = 0; sl < 2; ++sl) { const bf16x8 a = *(const bf16x8*)(Vl + (32 * b + r32) * VSTR + (32 * kb + 16 * sl + 8 * hi) * 2); o[b] = MFMA32(a, pb[sl], o[b]); }
;                 }
;             }
;         }
;         if (j + 1 < ntiles) AT_STORE((j + 1) & 1);
	v_sub_f32_e32 v111, v99, v116
	v_exp_f32_e32 v111, v111
	v_mul_f32_e32 v35, v35, v112
	v_add_u32_e32 v112, 34, v104
	v_cndmask_b32_e64 v34, v34, 0, s[14:15]
	v_mul_f32_e32 v38, v38, v111
	v_sub_f32_e32 v111, v99, v117
	v_exp_f32_e32 v111, v111
	s_and_b64 s[14:15], s[12:13], vcc
	v_cmp_gt_i32_e32 vcc, v112, v98
	v_add_u32_e32 v112, 35, v104
	v_mul_f32_e32 v39, v39, v111
	v_sub_f32_e32 v111, v99, v118
	v_exp_f32_e32 v111, v111
	v_cndmask_b32_e64 v35, v35, 0, s[14:15]
	s_and_b64 s[14:15], s[12:13], vcc
	v_cmp_gt_i32_e32 vcc, v112, v98
	v_add_u32_e32 v112, 36, v104
	v_mul_f32_e32 v40, v40, v111
	v_sub_f32_e32 v111, v99, v119
	v_cndmask_b32_e64 v36, v36, 0, s[14:15]
	s_and_b64 s[14:15], s[12:13], vcc
	v_cmp_gt_i32_e32 vcc, v112, v98
	v_add_u32_e32 v112, 37, v104
	v_exp_f32_e32 v111, v111
	v_cndmask_b32_e64 v37, v37, 0, s[14:15]
	s_and_b64 s[14:15], s[12:13], vcc
	v_cmp_gt_i32_e32 vcc, v112, v98
	v_add_u32_e32 v112, 38, v104
	v_cndmask_b32_e64 v38, v38, 0, s[14:15]
	s_and_b64 s[14:15], s[12:13], vcc
	v_cmp_gt_i32_e32 vcc, v112, v98
	v_add_u32_e32 v112, 39, v104
	v_cndmask_b32_e64 v39, v39, 0, s[14:15]
	s_and_b64 s[14:15], s[12:13], vcc
	v_cmp_gt_i32_e32 vcc, v112, v98
	v_cndmask_b32_e64 v40, v40, 0, s[14:15]
	s_and_b64 s[14:15], s[12:13], vcc
	v_mul_f32_e32 v41, v41, v111
	v_cndmask_b32_e64 v41, v41, 0, s[14:15]
	v_cvt_pk_bf16_f32 v34, v34, v35
	v_cvt_pk_bf16_f32 v35, v36, v37
	v_cvt_pk_bf16_f32 v36, v38, v39
	v_cvt_pk_bf16_f32 v37, v40, v41
	ds_read_b128 v[38:41], v110 offset:26816
	ds_read_b128 v[110:113], v110 offset:26832
	v_cmp_gt_i32_e32 vcc, v114, v98
	s_and_b64 s[14:15], s[12:13], vcc
	s_waitcnt lgkmcnt(1)
	v_sub_f32_e32 v38, v99, v38
	v_exp_f32_e32 v38, v38
	v_sub_f32_e32 v39, v99, v39
	v_exp_f32_e32 v39, v39
	v_sub_f32_e32 v40, v99, v40
	v_mul_f32_e32 v38, v42, v38
	v_add_u32_e32 v42, 49, v104
	v_cmp_gt_i32_e32 vcc, v42, v98
	v_add_u32_e32 v42, 50, v104
	v_cndmask_b32_e64 v38, v38, 0, s[14:15]
	s_and_b64 s[14:15], s[12:13], vcc
	v_mul_f32_e32 v39, v43, v39
	v_exp_f32_e32 v40, v40
	v_cmp_gt_i32_e32 vcc, v42, v98
	v_sub_f32_e32 v41, v99, v41
	v_add_u32_e32 v42, 51, v104
	v_cndmask_b32_e64 v39, v39, 0, s[14:15]
	s_and_b64 s[14:15], s[12:13], vcc
	v_exp_f32_e32 v41, v41
	v_cmp_gt_i32_e32 vcc, v42, v98
	s_waitcnt lgkmcnt(0)
	v_sub_f32_e32 v42, v99, v110
	v_exp_f32_e32 v42, v42
	v_mul_f32_e32 v40, v44, v40
	v_add_u32_e32 v43, 52, v104
	v_cndmask_b32_e64 v40, v40, 0, s[14:15]
	s_and_b64 s[14:15], s[12:13], vcc
	v_mul_f32_e32 v41, v45, v41
	v_cmp_gt_i32_e32 vcc, v43, v98
	v_sub_f32_e32 v43, v99, v111
	v_add_u32_e32 v44, 53, v104
	v_cndmask_b32_e64 v41, v41, 0, s[14:15]
	s_and_b64 s[14:15], s[12:13], vcc
	v_mul_f32_e32 v42, v46, v42
	v_exp_f32_e32 v43, v43
	v_cmp_gt_i32_e32 vcc, v44, v98
	v_add_u32_e32 v45, 54, v104
	v_cndmask_b32_e64 v42, v42, 0, s[14:15]
	s_and_b64 s[14:15], s[12:13], vcc
	v_sub_f32_e32 v44, v99, v112
	v_cmp_gt_i32_e32 vcc, v45, v98
	v_sub_f32_e32 v45, v99, v113
	v_exp_f32_e32 v44, v44
	v_exp_f32_e32 v45, v45
	v_mul_f32_e32 v43, v47, v43
	v_add_u32_e32 v46, 55, v104
	v_cndmask_b32_e64 v43, v43, 0, s[14:15]
	s_and_b64 s[14:15], s[12:13], vcc
	v_cmp_gt_i32_e32 vcc, v46, v98
	v_mul_f32_e32 v44, v48, v44
	s_and_b64 s[12:13], s[12:13], vcc
	v_mul_f32_e32 v45, v49, v45
	v_cndmask_b32_e64 v44, v44, 0, s[14:15]
	v_cndmask_b32_e64 v45, v45, 0, s[12:13]
	v_cvt_pk_bf16_f32 v38, v38, v39
	v_cvt_pk_bf16_f32 v39, v40, v41
	v_cvt_pk_bf16_f32 v40, v42, v43
	v_cvt_pk_bf16_f32 v41, v44, v45
	ds_read_b128 v[42:45], v105 offset:17472
	ds_read_b128 v[46:49], v105 offset:17504
	s_waitcnt lgkmcnt(1)
	v_mfma_f32_32x32x16_bf16 v[2:17], v[42:45], v[34:37], v[2:17]
	ds_read_b128 v[42:45], v105 offset:22080
	s_waitcnt lgkmcnt(0)
	v_mfma_f32_32x32x16_bf16 v[18:33], v[42:45], v[34:37], v[18:33]
	ds_read_b128 v[34:37], v105 offset:22112
	v_mfma_f32_32x32x16_bf16 v[2:17], v[46:49], v[38:41], v[2:17]
	s_waitcnt lgkmcnt(0)
	v_mfma_f32_32x32x16_bf16 v[18:33], v[34:37], v[38:41], v[18:33]
.LBB0_673:
	s_andn2_b64 vcc, exec, s[10:11]
	s_cbranch_vccnz .LBB0_679
	s_waitcnt vmcnt(0)
	v_mov_b32_e32 v82, v140
	v_mov_b32_e32 v83, v141
	v_mov_b32_e32 v84, v142
	v_mov_b32_e32 v85, v143
	v_mov_b32_e32 v86, v144
	v_mov_b32_e32 v87, v145
	v_mov_b32_e32 v88, v146
	v_mov_b32_e32 v89, v147
	v_mov_b32_e32 v90, v148
	v_mov_b32_e32 v91, v149
	v_mov_b32_e32 v92, v150
	v_mov_b32_e32 v93, v151
	v_mov_b32_e32 v94, v152
	v_mov_b32_e32 v95, v153
	v_mov_b32_e32 v96, v154
	v_mov_b32_e32 v97, v155
	v_mov_b32_e32 v140, v156
	v_mov_b32_e32 v141, v157
	v_mov_b32_e32 v142, v158
	v_mov_b32_e32 v143, v159
	v_mov_b32_e32 v144, v160
	v_mov_b32_e32 v145, v161
	v_mov_b32_e32 v146, v162
	v_mov_b32_e32 v147, v163
	v_mov_b32_e32 v148, v164
	v_mov_b32_e32 v149, v165
	v_mov_b32_e32 v150, v166
	v_mov_b32_e32 v151, v167
	v_mov_b32_e32 v152, v168
	v_mov_b32_e32 v153, v169
	v_mov_b32_e32 v154, v170
	v_mov_b32_e32 v155, v171
	v_mov_b32_e32 v156, v182
	v_mov_b32_e32 v157, v183
	v_mov_b32_e32 v158, v184
	v_mov_b32_e32 v159, v185
	v_mov_b32_e32 v160, v186
	v_mov_b32_e32 v161, v187
	v_mov_b32_e32 v162, v188
	v_mov_b32_e32 v163, v189
	v_mov_b32_e32 v164, v190
	v_mov_b32_e32 v165, v191
	v_mov_b32_e32 v166, v192
	v_mov_b32_e32 v167, v193
	v_mov_b32_e32 v168, v244
	v_mov_b32_e32 v169, v245
	v_mov_b32_e32 v170, v246
	v_mov_b32_e32 v171, v247
	v_mov_b32_e32 v34, v179
	s_bitcmp1_b32 s24, 0
	v_ashrrev_i32_e32 v35, 31, v34
	v_lshrrev_b32_e32 v36, 28, v35
	v_add_u32_e32 v36, v34, v36
	v_lshrrev_b32_e32 v37, 4, v36
	v_and_b32_e32 v36, 0xffffff0, v36
	s_cselect_b32 s4, 0x6900, 0
	v_sub_u32_e32 v36, v34, v36
	s_add_i32 s12, s4, 16
	v_mul_lo_u32 v37, v37, s97
	v_lshlrev_b32_e32 v36, 4, v36
	v_add3_u32 v36, s12, v37, v36
	s_waitcnt vmcnt(1)
	ds_write_b128 v36, v[82:85]
	v_add_u32_e32 v36, 0x200, v34
	v_ashrrev_i32_e32 v37, 31, v36
	v_lshrrev_b32_e32 v37, 28, v37
	v_add_u32_e32 v37, v36, v37
	v_lshrrev_b32_e32 v38, 4, v37
	v_and_b32_e32 v37, 0xffffff0, v37
	v_sub_u32_e32 v36, v36, v37
	v_mul_lo_u32 v38, v38, s97
	v_lshlrev_b32_e32 v36, 4, v36
	v_add3_u32 v36, s12, v38, v36
	v_cmp_gt_i32_e32 vcc, s41, v34
	s_waitcnt vmcnt(0)
	ds_write_b128 v36, v[86:89]
	s_and_saveexec_b64 s[10:11], vcc
	s_cbranch_execz .LBB0_676
	v_lshrrev_b32_e32 v35, 26, v35
	v_add_u32_e32 v35, v34, v35
	v_ashrrev_i32_e32 v36, 6, v35
	v_and_b32_e32 v35, 0xffc0, v35
	v_sub_u32_e32 v34, v34, v35
	v_lshrrev_b16_sdwa v35, v230, sext(v34) dst_sel:DWORD dst_unused:UNUSED_PAD src0_sel:DWORD src1_sel:BYTE_0
	v_and_b32_e32 v35, 31, v35
	v_add_u16_e32 v35, v34, v35
	v_ashrrev_i16_sdwa v37, v231, sext(v35) dst_sel:DWORD dst_unused:UNUSED_PAD src0_sel:DWORD src1_sel:BYTE_0
	v_and_b32_e32 v35, 0xe0, v35
	v_sub_u16_e32 v34, v34, v35
	v_bfe_i32 v34, v34, 0, 8
	v_bfe_i32 v35, v37, 0, 16
	v_lshl_add_u32 v34, v34, 1, v35
	v_mul_i32_i24_e32 v34, 0x90, v34
	v_lshlrev_b32_e32 v35, 4, v36
	v_add3_u32 v34, s12, v34, v35
	ds_write_b128 v34, v[90:93] offset:17408
